# x->out residual copy in P0 removed: first FFN norm and first down-GEMM residual epilogue read the input x directly (on top of v23)
# speedup vs baseline: 1.0093x; 1.0093x over previous
.LBB0_71:
	s_or_b64 exec, exec, s[2:3]
	v_lshl_add_u64 v[0:1], s[10:11], 0, v[132:133]
	s_mov_b64 s[0:1], 0x400000
	v_cmp_gt_u64_e32 vcc, s[0:1], v[0:1]
	s_mov_b64 s[2:3], exec
	v_readlane_b32 s16, v249, 34
	v_readlane_b32 s17, v249, 35
	v_readlane_b32 s18, v249, 36
	v_readlane_b32 s19, v249, 37
	v_readlane_b32 s20, v249, 38
	v_readlane_b32 s21, v249, 39
	v_readlane_b32 s22, v249, 40
	v_readlane_b32 s23, v249, 41
	v_readlane_b32 s24, v249, 42
	v_readlane_b32 s25, v249, 43
	v_readlane_b32 s26, v249, 44
	v_readlane_b32 s27, v249, 45
	v_readlane_b32 s12, v249, 2
	s_and_b64 s[0:1], s[2:3], vcc
	v_readlane_b32 s30, v249, 48
	v_readlane_b32 s31, v249, 49
	v_readlane_b32 s13, v249, 3
	v_readlane_b32 s28, v249, 46
	v_readlane_b32 s29, v249, 47
	v_readlane_b32 s14, v249, 4
	v_readlane_b32 s15, v249, 5
	v_readlane_b32 s16, v249, 6
	v_readlane_b32 s17, v249, 7
	v_readlane_b32 s18, v249, 8
	v_readlane_b32 s19, v249, 9
	v_readlane_b32 s20, v249, 10
	v_readlane_b32 s21, v249, 11
	v_readlane_b32 s22, v249, 12
	v_readlane_b32 s23, v249, 13
	v_readlane_b32 s24, v249, 14
	v_readlane_b32 s25, v249, 15
	v_readlane_b32 s26, v249, 16
	v_readlane_b32 s27, v249, 17
	s_mov_b64 exec, s[0:1]
.LBB0_74:
	s_or_b64 exec, exec, s[2:3]
	s_add_u32 s96, s92, 0xa000000
	s_mov_b64 s[0:1], 0x20000
	s_addc_u32 s97, s93, 0
	v_cmp_gt_u64_e32 vcc, s[0:1], v[0:1]
	s_and_saveexec_b64 s[2:3], vcc
	v_readlane_b32 s8, v249, 2
	v_readlane_b32 s12, v249, 6
	v_readlane_b32 s13, v249, 7
	v_readlane_b32 s9, v249, 3
	v_readlane_b32 s10, v249, 4
	v_readlane_b32 s11, v249, 5
	v_readlane_b32 s14, v249, 8
	v_readlane_b32 s15, v249, 9
	v_readlane_b32 s16, v249, 10
	v_readlane_b32 s17, v249, 11
	v_readlane_b32 s18, v249, 12
	v_readlane_b32 s19, v249, 13
	v_readlane_b32 s20, v249, 14
	v_readlane_b32 s21, v249, 15
	v_readlane_b32 s22, v249, 16
	v_readlane_b32 s23, v249, 17
	s_cbranch_execz .LBB0_77
	s_ashr_i32 s1, s94, 31
	s_mov_b32 s0, s94
	s_lshl_b64 s[6:7], s[52:53], 13
	s_lshl_b64 s[4:5], s[0:1], 9
	v_lshl_add_u64 v[2:3], v[132:133], 4, s[6:7]
	s_lshl_b64 s[6:7], s[0:1], 13
	s_mov_b64 s[8:9], 0
	s_mov_b64 s[10:11], 0x1ffff

.LBB0_1099:
	v_readlane_b32 s6, v255, 14
	v_readlane_b32 s7, v255, 15
	s_xor_b64 s[4:5], s[6:7], -1
	v_writelane_b32 v255, s4, 16
	s_movk_i32 s1, 0x4000
	s_waitcnt vmcnt(8)
	v_mov_b32_e32 v18, v198
	v_writelane_b32 v255, s5, 17
	v_readlane_b32 s4, v254, 49
	v_readlane_b32 s5, v254, 50
	s_or_b64 s[44:45], s[4:5], s[6:7]
	s_and_b64 s[4:5], s[44:45], exec
	s_cselect_b32 s12, 0x4200, s1
	v_readlane_b32 s4, v253, 40
	s_cmp_lt_i32 s4, s12
	v_readlane_b32 s5, v253, 41
	s_cbranch_scc0 .LBB0_1106
	s_cmp_lg_u32 s2, 0
	s_cselect_b64 s[4:5], -1, 0
	s_lshl_b32 s0, s0, 2
	v_readlane_b32 s1, v254, 45
	v_readlane_b32 s64, v249, 2
	s_add_u32 s0, s1, s0
	v_readlane_b32 s1, v254, 47
	v_readlane_b32 s6, v255, 14
	v_readlane_b32 s65, v249, 3
	v_readlane_b32 s66, v249, 4
	v_readlane_b32 s67, v249, 5
	v_readlane_b32 s68, v249, 6
	v_readlane_b32 s69, v249, 7
	v_readlane_b32 s70, v249, 8
	v_readlane_b32 s71, v249, 9
	v_readlane_b32 s72, v249, 10
	v_readlane_b32 s73, v249, 11
	v_readlane_b32 s74, v249, 12
	v_readlane_b32 s75, v249, 13
	v_readlane_b32 s76, v249, 14
	v_readlane_b32 s77, v249, 15
	v_readlane_b32 s78, v249, 16
	v_readlane_b32 s79, v249, 17
	s_addc_u32 s1, s1, 0
	v_readlane_b32 s7, v255, 15
	s_mov_b64 s[16:17], s[76:77]
	v_readlane_b32 s64, v249, 34
	s_and_b64 s[6:7], exec, s[6:7]
	v_readlane_b32 s70, v249, 40
	v_lshlrev_b32_e32 v0, 2, v18
	v_readlane_b32 s71, v249, 41
	s_cselect_b32 s6, s16, s70
	v_readlane_b32 s8, v254, 10
	v_and_b32_e32 v20, 0xfc, v0
	s_cselect_b32 s3, s17, s71
	v_readlane_b32 s9, v254, 11
	s_add_u32 s6, s6, s8
	v_lshlrev_b32_e32 v0, 2, v20
	s_addc_u32 s7, s3, s9
	global_load_dwordx4 v[2:5], v0, s[6:7]
	global_load_dwordx4 v[6:9], v0, s[6:7] offset:1024
	global_load_dwordx4 v[10:13], v0, s[6:7] offset:2048
	global_load_dwordx4 v[14:17], v0, s[6:7] offset:3072
	v_cmp_lt_i32_e32 vcc, v204, v203
	v_lshl_add_u64 v[34:35], s[96:97], 0, v[0:1]
	v_readlane_b32 s6, v249, 50
	v_cndmask_b32_e32 v0, v202, v204, vcc
	v_cmp_lt_i32_e32 vcc, v205, v203
	v_lshlrev_b32_e32 v42, 2, v0
	v_readlane_b32 s7, v249, 51
	v_cndmask_b32_e32 v0, v202, v205, vcc
	v_cmp_lt_i32_e32 vcc, v206, v203
	v_lshlrev_b32_e32 v43, 2, v0
	v_readlane_b32 s72, v249, 42
	v_cndmask_b32_e32 v0, v202, v206, vcc
	v_lshlrev_b32_e32 v44, 2, v0
	v_xor_b32_e32 v0, 8, v202
	v_cmp_lt_i32_e32 vcc, v0, v203
	v_readlane_b32 s73, v249, 43
	v_readlane_b32 s74, v249, 44
	v_cndmask_b32_e32 v0, v202, v0, vcc
	v_cmp_lt_i32_e32 vcc, v208, v203
	v_lshlrev_b32_e32 v45, 2, v0
	v_readlane_b32 s75, v249, 45
	v_cndmask_b32_e32 v0, v202, v208, vcc
	v_cmp_lt_i32_e32 vcc, v209, v203
	v_lshlrev_b32_e32 v46, 2, v0
	v_readlane_b32 s76, v249, 46
	v_cndmask_b32_e32 v0, v202, v209, vcc
	v_lshlrev_b32_e32 v47, 2, v0
	v_lshlrev_b32_e32 v0, 1, v20
	v_readlane_b32 s77, v249, 47
	v_lshl_add_u64 v[36:37], s[6:7], 0, v[0:1]
	v_and_b32_e32 v0, 63, v18
	v_readlane_b32 s76, v253, 60
	v_readlane_b32 s74, v253, 58
	v_readlane_b32 s72, v253, 56
	v_readlane_b32 s70, v253, 54
	v_or_b32_e32 v22, 0x100, v20
	v_or_b32_e32 v24, 0x200, v20
	v_or_b32_e32 v26, 0x300, v20
	v_lshlrev_b32_e32 v0, 4, v0
	v_readlane_b32 s65, v249, 35
	v_readlane_b32 s66, v249, 36
	v_readlane_b32 s67, v249, 37
	v_readlane_b32 s68, v249, 38
	v_readlane_b32 s69, v249, 39
	v_readlane_b32 s78, v249, 48
	v_readlane_b32 s79, v249, 49
	v_readlane_b32 s98, v249, 2
	v_readlane_b32 s99, v249, 3
	v_readlane_b32 s77, v253, 61
	v_readlane_b32 s75, v253, 59
	v_readlane_b32 s73, v253, 57
	v_readlane_b32 s71, v253, 55
	v_readlane_b32 s62, v253, 53
	s_lshl_b32 s13, s2, 21
	v_lshl_add_u64 v[38:39], s[92:93], 0, v[0:1]
	s_xor_b64 s[2:3], s[4:5], -1
	v_lshlrev_b32_e32 v48, 2, v20
	v_lshlrev_b32_e32 v49, 2, v22
	v_lshlrev_b32_e32 v50, 2, v24
	v_lshlrev_b32_e32 v51, 2, v26
	v_readlane_b32 s4, v253, 42
	v_readlane_b32 s6, v253, 40
	v_readlane_b32 s7, v253, 41
	s_branch .LBB0_1102

.LBB0_1102:
	s_add_i32 s14, s6, 0xffffc000
	s_ashr_i32 s7, s6, 31
	s_cmpk_lt_i32 s6, 0x4000
	s_cselect_b64 s[8:9], -1, 0
	s_and_b64 s[10:11], s[8:9], exec
	s_cselect_b32 s11, s7, 0
	s_cselect_b32 s10, s6, s14
	s_cselect_b32 s5, s99, s97
	s_cselect_b32 s16, s98, s96
	s_lshl_b64 s[10:11], s[10:11], 12
	s_add_u32 s10, s16, s10
	s_addc_u32 s11, s5, s11
	global_load_dwordx4 v[30:33], v48, s[10:11]
	global_load_dwordx4 v[26:29], v48, s[10:11] offset:1024
	global_load_dwordx4 v[22:25], v48, s[10:11] offset:2048
	global_load_dwordx4 v[18:21], v48, s[10:11] offset:3072
	s_or_b64 s[8:9], s[2:3], s[8:9]
	s_and_b64 vcc, exec, s[8:9]
	s_cbranch_vccnz .LBB0_1101
	s_mov_b32 s5, s15
	s_lshl_b64 s[8:9], s[4:5], 12
	v_lshl_add_u64 v[40:41], v[38:39], 0, s[8:9]
	s_mov_b64 s[8:9], 0
	s_cmp_eq_u32 s13, 0x1600000
	s_cbranch_scc1 .Lfold_b11
	s_cmp_eq_u32 s13, 0x800000
	s_cbranch_scc1 .Lfold_b4
	s_branch .LBB0_1104

.LBB0_1250:
	v_readlane_b32 s98, v249, 2
	v_readlane_b32 s99, v249, 3
	s_sub_i32 s0, s37, 64
	s_ashr_i32 s1, s37, 31
	s_cmp_lt_i32 s37, 64
	s_cselect_b32 s1, s1, 0
	s_cselect_b32 s0, s37, s0
	s_movk_i32 s8, 0x4800
	s_cselect_b32 s2, s79, s97
	s_cselect_b32 s3, s78, s96
	s_cselect_b32 s99, s99, s97
	s_cselect_b32 s98, s98, s96
	s_cselect_b32 s8, 0x2400, s8
	s_lshl_b64 s[0:1], s[0:1], 20
	s_add_u32 s98, s98, s0
	s_addc_u32 s99, s99, s1
	s_add_u32 s0, s3, s0
	s_addc_u32 s1, s2, s1
	s_cmp_gt_i32 s37, 31
	s_cselect_b32 s2, s8, 0
	s_lshl_b32 s2, s2, 2
	v_lshl_or_b32 v152, s36, 8, v157
	s_add_u32 s2, s29, s2
	v_ashrrev_i32_e32 v153, 31, v152
	s_addc_u32 s3, s30, 0
	v_lshlrev_b64 v[152:153], 2, v[152:153]
	global_load_dwordx4 v[160:163], v152, s[2:3]
	global_load_dwordx4 v[164:167], v152, s[2:3] offset:64
	global_load_dwordx4 v[168:171], v152, s[2:3] offset:512
	global_load_dwordx4 v[172:175], v152, s[2:3] offset:576
	v_add_u32_e32 v159, v152, v132
	v_add_u32_e32 v153, v152, v136
	v_add_u32_e32 v196, v152, v138
	v_add_u32_e32 v197, v152, v140
	v_add_u32_e32 v234, v152, v134
	v_add_u32_e32 v235, v152, v142
	v_add_u32_e32 v210, v152, v144
	v_add_u32_e32 v211, v152, v146
	global_load_dwordx4 v[176:179], v159, s[98:99]
	global_load_dwordx4 v[180:183], v153, s[98:99]
	global_load_dwordx4 v[184:187], v196, s[98:99]
	global_load_dwordx4 v[188:191], v197, s[98:99]
	global_load_dwordx4 v[192:195], v234, s[98:99]
	global_load_dwordx4 v[214:217], v235, s[98:99]
	global_load_dwordx4 v[218:221], v210, s[98:99]
	global_load_dwordx4 v[222:225], v211, s[98:99]
	global_load_dwordx4 v[226:229], v159, s[98:99] offset:64
	global_load_dwordx4 v[230:233], v153, s[98:99] offset:64
	global_load_dwordx4 v[240:243], v196, s[98:99] offset:64
	global_load_dwordx4 v[244:247], v197, s[98:99] offset:64
	v_readlane_b32 s18, v249, 56
	s_mov_b64 s[2:3], -1
	s_and_b64 vcc, exec, s[38:39]
	v_readlane_b32 s19, v249, 57
	s_waitcnt vmcnt(11)
	v_pk_mul_f32 v[160:161], v[160:161], 0.5 op_sel_hi:[1,0]
	v_pk_mul_f32 v[162:163], v[162:163], 0.5 op_sel_hi:[1,0]
	v_pk_fma_f32 v[128:129], v[128:129], v[162:163], v[178:179]
	v_pk_fma_f32 v[126:127], v[126:127], v[160:161], v[176:177]
	global_store_dwordx4 v159, v[126:129], s[0:1] sc1
	s_nop 1
	global_load_dwordx4 v[126:129], v234, s[98:99] offset:64
	s_waitcnt vmcnt(12)
	v_pk_fma_f32 v[124:125], v[124:125], v[162:163], v[182:183]
	v_pk_fma_f32 v[122:123], v[122:123], v[160:161], v[180:181]
	global_store_dwordx4 v153, v[122:125], s[0:1] sc1
	s_nop 1
	global_load_dwordx4 v[122:125], v235, s[98:99] offset:64
	s_waitcnt vmcnt(13)
	v_pk_fma_f32 v[120:121], v[120:121], v[162:163], v[186:187]
	v_pk_fma_f32 v[118:119], v[118:119], v[160:161], v[184:185]
	global_store_dwordx4 v196, v[118:121], s[0:1] sc1
	s_nop 1
	global_load_dwordx4 v[118:121], v210, s[98:99] offset:64
	s_waitcnt vmcnt(14)
	v_pk_fma_f32 v[116:117], v[116:117], v[162:163], v[190:191]
	v_pk_fma_f32 v[114:115], v[114:115], v[160:161], v[188:189]
	global_store_dwordx4 v197, v[114:117], s[0:1] sc1
	s_nop 1
	global_load_dwordx4 v[114:117], v211, s[98:99] offset:64
	s_waitcnt vmcnt(15)
	v_pk_fma_f32 v[112:113], v[112:113], v[162:163], v[194:195]
	v_pk_fma_f32 v[110:111], v[110:111], v[160:161], v[192:193]
	global_store_dwordx4 v234, v[110:113], s[0:1] sc1
	s_nop 1
	global_load_dwordx4 v[110:113], v159, s[98:99] offset:512
	s_waitcnt vmcnt(16)
	v_pk_fma_f32 v[108:109], v[108:109], v[162:163], v[216:217]
	v_pk_fma_f32 v[106:107], v[106:107], v[160:161], v[214:215]
	global_store_dwordx4 v235, v[106:109], s[0:1] sc1
	s_nop 1
	global_load_dwordx4 v[106:109], v153, s[98:99] offset:512
	s_waitcnt vmcnt(17)
	v_pk_fma_f32 v[104:105], v[104:105], v[162:163], v[220:221]
	v_pk_fma_f32 v[102:103], v[102:103], v[160:161], v[218:219]
	global_store_dwordx4 v210, v[102:105], s[0:1] sc1
	s_nop 1
	global_load_dwordx4 v[102:105], v196, s[98:99] offset:512
	s_waitcnt vmcnt(18)
	v_pk_fma_f32 v[96:97], v[96:97], v[162:163], v[224:225]
	v_pk_fma_f32 v[94:95], v[94:95], v[160:161], v[222:223]
	global_store_dwordx4 v211, v[94:97], s[0:1] sc1
	s_nop 1
	global_load_dwordx4 v[94:97], v197, s[98:99] offset:512
	s_waitcnt vmcnt(19)
	v_pk_mul_f32 v[164:165], v[164:165], 0.5 op_sel_hi:[1,0]
	v_pk_mul_f32 v[166:167], v[166:167], 0.5 op_sel_hi:[1,0]
	v_pk_fma_f32 v[100:101], v[100:101], v[166:167], v[228:229]
	v_pk_fma_f32 v[98:99], v[98:99], v[164:165], v[226:227]
	global_store_dwordx4 v159, v[98:101], s[0:1] offset:64 sc1
	s_nop 1
	global_load_dwordx4 v[98:101], v234, s[98:99] offset:512
	s_waitcnt vmcnt(20)
	v_pk_fma_f32 v[92:93], v[92:93], v[166:167], v[232:233]
	v_pk_fma_f32 v[90:91], v[90:91], v[164:165], v[230:231]
	global_store_dwordx4 v153, v[90:93], s[0:1] offset:64 sc1
	s_nop 1
	global_load_dwordx4 v[90:93], v235, s[98:99] offset:512
	s_waitcnt vmcnt(21)
	v_pk_fma_f32 v[88:89], v[88:89], v[166:167], v[242:243]
	v_pk_fma_f32 v[86:87], v[86:87], v[164:165], v[240:241]
	global_store_dwordx4 v196, v[86:89], s[0:1] offset:64 sc1
	s_nop 1
	global_load_dwordx4 v[86:89], v210, s[98:99] offset:512
	s_waitcnt vmcnt(22)
	v_pk_fma_f32 v[84:85], v[84:85], v[166:167], v[246:247]
	v_pk_fma_f32 v[82:83], v[82:83], v[164:165], v[244:245]
	global_store_dwordx4 v197, v[82:85], s[0:1] offset:64 sc1
	s_nop 1
	global_load_dwordx4 v[82:85], v211, s[98:99] offset:512
	s_waitcnt vmcnt(22)
	v_pk_fma_f32 v[80:81], v[80:81], v[166:167], v[128:129]
	v_pk_fma_f32 v[78:79], v[78:79], v[164:165], v[126:127]
	global_store_dwordx4 v234, v[78:81], s[0:1] offset:64 sc1
	s_nop 1
	global_load_dwordx4 v[78:81], v159, s[98:99] offset:576
	s_waitcnt vmcnt(22)
	v_pk_fma_f32 v[76:77], v[76:77], v[166:167], v[124:125]
	v_pk_fma_f32 v[74:75], v[74:75], v[164:165], v[122:123]
	global_store_dwordx4 v235, v[74:77], s[0:1] offset:64 sc1
	s_nop 1
	global_load_dwordx4 v[74:77], v153, s[98:99] offset:576
	s_waitcnt vmcnt(22)
	v_pk_fma_f32 v[72:73], v[72:73], v[166:167], v[120:121]
	v_pk_fma_f32 v[70:71], v[70:71], v[164:165], v[118:119]
	global_store_dwordx4 v210, v[70:73], s[0:1] offset:64 sc1
	s_nop 1
	global_load_dwordx4 v[70:73], v196, s[98:99] offset:576
	s_waitcnt vmcnt(22)
	v_pk_fma_f32 v[64:65], v[64:65], v[166:167], v[116:117]
	v_pk_fma_f32 v[62:63], v[62:63], v[164:165], v[114:115]
	global_store_dwordx4 v211, v[62:65], s[0:1] offset:64 sc1
	s_nop 1
	global_load_dwordx4 v[62:65], v197, s[98:99] offset:576
	s_waitcnt vmcnt(22)
	v_pk_mul_f32 v[168:169], v[168:169], 0.5 op_sel_hi:[1,0]
	v_pk_mul_f32 v[170:171], v[170:171], 0.5 op_sel_hi:[1,0]
	v_pk_fma_f32 v[68:69], v[68:69], v[170:171], v[112:113]
	v_pk_fma_f32 v[66:67], v[66:67], v[168:169], v[110:111]
	global_store_dwordx4 v159, v[66:69], s[0:1] offset:512 sc1
	s_nop 1
	global_load_dwordx4 v[66:69], v234, s[98:99] offset:576
	s_waitcnt vmcnt(22)
	v_pk_fma_f32 v[60:61], v[60:61], v[170:171], v[108:109]
	v_pk_fma_f32 v[58:59], v[58:59], v[168:169], v[106:107]
	global_store_dwordx4 v153, v[58:61], s[0:1] offset:512 sc1
	s_nop 1
	global_load_dwordx4 v[58:61], v235, s[98:99] offset:576
	s_waitcnt vmcnt(22)
	v_pk_fma_f32 v[56:57], v[56:57], v[170:171], v[104:105]
	v_pk_fma_f32 v[54:55], v[54:55], v[168:169], v[102:103]
	global_store_dwordx4 v196, v[54:57], s[0:1] offset:512 sc1
	s_nop 1
	global_load_dwordx4 v[54:57], v210, s[98:99] offset:576
	s_waitcnt vmcnt(22)
	v_pk_fma_f32 v[52:53], v[52:53], v[170:171], v[96:97]
	v_pk_fma_f32 v[50:51], v[50:51], v[168:169], v[94:95]
	global_store_dwordx4 v197, v[50:53], s[0:1] offset:512 sc1
	s_nop 1
	global_load_dwordx4 v[50:53], v211, s[98:99] offset:576
	s_waitcnt vmcnt(22)
	v_pk_fma_f32 v[48:49], v[48:49], v[170:171], v[100:101]
	v_pk_fma_f32 v[46:47], v[46:47], v[168:169], v[98:99]
	global_store_dwordx4 v234, v[46:49], s[0:1] offset:512 sc1
	s_waitcnt vmcnt(21)
	v_pk_fma_f32 v[44:45], v[44:45], v[170:171], v[92:93]
	v_pk_fma_f32 v[42:43], v[42:43], v[168:169], v[90:91]
	global_store_dwordx4 v235, v[42:45], s[0:1] offset:512 sc1
	s_waitcnt vmcnt(20)
	v_pk_fma_f32 v[40:41], v[40:41], v[170:171], v[88:89]
	v_pk_fma_f32 v[38:39], v[38:39], v[168:169], v[86:87]
	global_store_dwordx4 v210, v[38:41], s[0:1] offset:512 sc1
	s_waitcnt vmcnt(19)
	v_pk_fma_f32 v[32:33], v[32:33], v[170:171], v[84:85]
	v_pk_fma_f32 v[30:31], v[30:31], v[168:169], v[82:83]
	global_store_dwordx4 v211, v[30:33], s[0:1] offset:512 sc1
	s_waitcnt vmcnt(18)
	v_pk_mul_f32 v[172:173], v[172:173], 0.5 op_sel_hi:[1,0]
	v_pk_mul_f32 v[174:175], v[174:175], 0.5 op_sel_hi:[1,0]
	v_pk_fma_f32 v[36:37], v[36:37], v[174:175], v[80:81]
	v_pk_fma_f32 v[34:35], v[34:35], v[172:173], v[78:79]
	global_store_dwordx4 v159, v[34:37], s[0:1] offset:576 sc1
	s_waitcnt vmcnt(17)
	v_pk_fma_f32 v[28:29], v[28:29], v[174:175], v[76:77]
	v_pk_fma_f32 v[26:27], v[26:27], v[172:173], v[74:75]
	global_store_dwordx4 v153, v[26:29], s[0:1] offset:576 sc1
	s_waitcnt vmcnt(16)
	v_pk_fma_f32 v[24:25], v[24:25], v[174:175], v[72:73]
	v_pk_fma_f32 v[22:23], v[22:23], v[172:173], v[70:71]
	global_store_dwordx4 v196, v[22:25], s[0:1] offset:576 sc1
	s_waitcnt vmcnt(15)
	v_pk_fma_f32 v[20:21], v[20:21], v[174:175], v[64:65]
	v_pk_fma_f32 v[18:19], v[18:19], v[172:173], v[62:63]
	global_store_dwordx4 v197, v[18:21], s[0:1] offset:576 sc1
	s_waitcnt vmcnt(14)
	v_pk_fma_f32 v[16:17], v[16:17], v[174:175], v[68:69]
	v_pk_fma_f32 v[14:15], v[14:15], v[172:173], v[66:67]
	global_store_dwordx4 v234, v[14:17], s[0:1] offset:576 sc1
	s_waitcnt vmcnt(13)
	v_pk_fma_f32 v[12:13], v[12:13], v[174:175], v[60:61]
	v_pk_fma_f32 v[10:11], v[10:11], v[172:173], v[58:59]
	global_store_dwordx4 v235, v[10:13], s[0:1] offset:576 sc1
	s_waitcnt vmcnt(12)
	v_pk_fma_f32 v[8:9], v[8:9], v[174:175], v[56:57]
	v_pk_fma_f32 v[6:7], v[6:7], v[172:173], v[54:55]
	global_store_dwordx4 v210, v[6:9], s[0:1] offset:576 sc1
	s_waitcnt vmcnt(11)
	v_pk_fma_f32 v[4:5], v[4:5], v[174:175], v[52:53]
	v_pk_fma_f32 v[2:3], v[2:3], v[172:173], v[50:51]
	global_store_dwordx4 v211, v[2:5], s[0:1] offset:576 sc1
	s_cbranch_vccnz .LBB0_1235
	s_andn2_b64 vcc, exec, s[42:43]
	s_cbranch_vccnz .LBB0_1234
	s_barrier
	s_branch .LBB0_1234
.LBB0_1253:
	v_readlane_b32 s98, v249, 48
	v_readlane_b32 s99, v249, 49
	s_nop 3
	v_writelane_b32 v249, s98, 2
	v_writelane_b32 v249, s99, 3
	s_waitcnt vmcnt(0)
	v_readlane_b32 s30, v254, 4
	v_readlane_b32 s34, v254, 6
	v_readlane_b32 s31, v254, 5
	v_readlane_b32 s35, v254, 7
	s_barrier
